# retB look-back rewritten by hand: 16-chunk-deep software pipeline (static slots indexed from the end), same f32 Horner order
# speedup vs baseline: 1.0036x; 1.0023x over previous
.LBB0_567:
	s_xor_b64 s[42:43], s[0:1], -1
	s_lshr_b32 s0, s88, 2
	s_and_b32 s44, s0, 0x3ffffff8
	s_or_b32 s40, s44, s53
	s_lshl_b32 s36, s40, 6
	s_mov_b32 s37, 0
	s_bfe_u32 s52, s88, 0x20003
	s_lshl_b64 s[0:1], s[36:37], 2
	s_add_u32 s0, s96, s0
	s_addc_u32 s1, s97, s1
	s_add_u32 s38, s0, 0x84000
	s_addc_u32 s39, s1, 0
	s_cmp_lt_i32 s76, 4
	s_cselect_b64 s[0:1], -1, 0
	s_and_b64 s[24:25], s[0:1], s[2:3]
	s_andn2_b64 vcc, exec, s[24:25]
	v_lshlrev_b32_e32 v230, 3, v226
	v_lshrrev_b32_e32 v205, 3, v226
	v_and_b32_e32 v228, 31, v226
	v_lshrrev_b32_e32 v229, 5, v227
	v_lshlrev_b32_e32 v192, 4, v226
	s_cbranch_vccnz .LBB0_706
	s_lshl_b32 s0, s88, 1
	s_and_b32 s8, s0, 0x7fffff80
	s_lshl_b32 s9, s52, 5
	s_lshl_b32 s30, s40, 1
	s_and_b32 s5, s30, 30
	s_or_b32 s0, s9, s8
	s_or_b32 s2, s5, s0
	s_add_u32 s26, s96, 0x5500000
	s_addc_u32 s27, s97, 0
	s_lshr_b32 s36, s88, 6
	v_readlane_b32 s3, v254, 5
	s_lshl_b64 s[34:35], s[36:37], 12
	s_lshl_b32 s1, s5, 7
	v_lshrrev_b32_e32 v152, 4, v226
	v_add_u32_e32 v18, 0x200, v226
	v_add_u32_e32 v10, 0x600, v226
	s_lshr_b32 s4, s3, 7
	s_or_b32 s34, s34, s1
	s_lshl_b32 s36, s52, 7
	v_and_b32_e32 v2, 0x78, v230
	s_lshl_b32 s28, s52, 8
	v_lshrrev_b32_e32 v153, 4, v18
	v_or_b32_e32 v154, 64, v152
	v_lshrrev_b32_e32 v122, 4, v10
	s_lshl_b32 s31, s52, 6
	s_lshl_b32 s41, s4, 5
	v_or_b32_e32 v0, s34, v152
	s_movk_i32 s1, 0x1800
	v_mov_b64_e32 v[24:25], s[26:27]
	v_lshlrev_b32_e32 v118, 1, v2
	v_or_b32_e32 v2, s34, v153
	v_or_b32_e32 v8, s34, v154
	v_or_b32_e32 v10, s34, v122
	v_lshrrev_b32_e32 v116, 3, v18
	s_add_u32 s3, s34, s41
	v_mad_u64_u32 v[0:1], s[6:7], v0, s1, v[24:25]
	v_mov_b32_e32 v28, 0x1800
	v_mad_u64_u32 v[2:3], s[6:7], v2, s1, v[24:25]
	v_mad_u64_u32 v[8:9], s[6:7], v8, s1, v[24:25]
	v_mad_u64_u32 v[10:11], s[6:7], v10, s1, v[24:25]
	v_and_b32_e32 v19, 56, v230
	v_or_b32_e32 v16, s34, v205
	v_or_b32_e32 v18, s34, v116
	v_or_b32_e32 v26, s3, v228
	v_mov_b32_e32 v117, 0
	v_mad_u32_u24 v1, s35, v28, v1
	s_mov_b32 s29, s37
	v_mad_u32_u24 v3, s35, v28, v3
	v_mad_u32_u24 v9, s35, v28, v9
	v_mad_u32_u24 v11, s35, v28, v11
	v_mad_u64_u32 v[16:17], s[6:7], v16, s1, v[24:25]
	v_lshlrev_b32_e32 v120, 1, v19
	v_mad_u64_u32 v[18:19], s[6:7], v18, s1, v[24:25]
	s_addc_u32 s10, s35, 0
	v_mad_u64_u32 v[26:27], s[6:7], v26, s1, v[24:25]
	v_lshl_add_u64 v[0:1], v[0:1], 0, s[28:29]
	v_mov_b32_e32 v119, v117
	v_lshl_add_u64 v[2:3], v[2:3], 0, s[28:29]
	v_lshl_add_u64 v[8:9], v[8:9], 0, s[28:29]
	v_lshl_add_u64 v[10:11], v[10:11], 0, s[28:29]
	v_mad_u32_u24 v17, s35, v28, v17
	v_mad_u32_u24 v19, s35, v28, v19
	v_mad_u32_u24 v27, s10, v28, v27
	v_lshrrev_b32_e32 v112, 2, v226
	v_lshl_add_u64 v[0:1], v[0:1], 0, v[118:119]
	v_lshl_add_u64 v[2:3], v[2:3], 0, v[118:119]
	v_lshl_add_u64 v[8:9], v[8:9], 0, v[118:119]
	v_lshl_add_u64 v[10:11], v[10:11], 0, v[118:119]
	v_lshl_add_u64 v[16:17], v[16:17], 0, s[36:37]
	v_mov_b32_e32 v121, v117
	v_lshl_add_u64 v[18:19], v[18:19], 0, s[36:37]
	v_lshl_add_u64 v[26:27], v[26:27], 0, s[36:37]
	v_lshlrev_b32_e32 v126, 4, v229
	v_mov_b32_e32 v127, v117
	v_or_b32_e32 v119, s34, v112
	v_lshl_add_u64 v[16:17], v[16:17], 0, v[120:121]
	v_lshl_add_u64 v[18:19], v[18:19], 0, v[120:121]
	v_lshl_add_u64 v[26:27], v[26:27], 0, v[126:127]
	v_mad_u64_u32 v[24:25], s[6:7], v119, s1, v[24:25]
	global_load_dwordx4 v[4:7], v[0:1], off offset:1024
	s_nop 0
	global_load_dwordx4 v[0:3], v[2:3], off offset:1024
	s_nop 0
	global_load_dwordx4 v[12:15], v[8:9], off offset:1024
	s_nop 0
	global_load_dwordx4 v[8:11], v[10:11], off offset:1024
	s_nop 0
	global_load_dwordx4 v[20:23], v[16:17], off offset:512
	s_nop 0
	global_load_dwordx4 v[16:19], v[18:19], off offset:512
	s_nop 0
	global_load_dwordx4 v[72:75], v[26:27], off
	global_load_dwordx4 v[76:79], v[26:27], off offset:32
	global_load_dwordx4 v[80:83], v[26:27], off offset:64
	global_load_dwordx4 v[84:87], v[26:27], off offset:96
	v_lshlrev_b32_e32 v26, 5, v226
	s_add_u32 s7, s96, 0xe500000
	s_mov_b32 s3, s37
	v_mad_u32_u24 v25, s35, v28, v25
	v_and_b32_e32 v121, 0x60, v26
	s_addc_u32 s10, s97, 0
	s_lshl_b64 s[2:3], s[2:3], 14
	v_lshl_add_u64 v[24:25], v[24:25], 0, s[28:29]
	v_lshlrev_b32_e32 v114, 1, v121
	v_mov_b32_e32 v115, v117
	s_add_u32 s2, s7, s2
	v_lshl_add_u64 v[24:25], v[24:25], 0, v[114:115]
	s_addc_u32 s3, s10, s3
	v_mov_b32_e32 v193, v117
	global_load_dwordx4 v[56:59], v[24:25], off offset:2096
	global_load_dwordx4 v[60:63], v[24:25], off offset:2080
	global_load_dwordx4 v[64:67], v[24:25], off offset:2064
	global_load_dwordx4 v[68:71], v[24:25], off offset:2048
	v_lshl_add_u64 v[24:25], s[2:3], 0, v[192:193]
	v_add_co_u32_e32 v24, vcc, 0x2000, v24
	v_lshlrev_b32_e32 v155, 3, v229
	s_nop 0
	v_addc_co_u32_e32 v25, vcc, 0, v25, vcc
	global_load_dwordx4 v[52:55], v192, s[2:3]
	global_load_dwordx4 v[48:51], v[24:25], off
	v_cvt_f32_ubyte0_e32 v24, s52
	v_sub_f32_e32 v24, 0xc0a00000, v24
	v_exp_f32_e32 v24, v24
	v_mov_b32_e32 v113, v117
	s_movk_i32 s6, 0x2000
	s_cmp_eq_u32 s5, 0
	v_sub_f32_e32 v24, 1.0, v24
	v_log_f32_e32 v151, v24
	v_mov_b32_e32 v128, v117
	v_mov_b32_e32 v129, v117
	v_mov_b32_e32 v130, v117
	v_mul_f32_e32 v24, 0x43000000, v151
	v_exp_f32_e32 v124, v24
	v_mov_b32_e32 v131, v117
	v_mov_b32_e32 v132, v117
	v_mov_b32_e32 v133, v117
	v_mov_b32_e32 v144, v117
	v_mov_b32_e32 v145, v117
	v_mov_b32_e32 v142, v117
	v_mov_b32_e32 v143, v117
	v_mov_b32_e32 v140, v117
	v_mov_b32_e32 v141, v117
	v_mov_b32_e32 v138, v117
	v_mov_b32_e32 v139, v117
	v_mov_b32_e32 v136, v117
	v_mov_b32_e32 v137, v117
	s_cbranch_scc1 .LBB0_585
	s_mov_b32 s1, 0
	s_lshl_b64 s[2:3], s[0:1], 14
	s_add_u32 s2, s7, s2
	s_addc_u32 s3, s10, s3
	v_mov_b32_e32 v125, v124
	v_add_u32_e32 v134, 0x2000, v192
	s_add_i32 s6, s5, -16
	s_cmp_gt_u32 s5, 16
	s_cbranch_scc1 .Llbt1_Llb_iss
	s_cmp_gt_u32 s5, 8
	s_cbranch_scc1 .Llbt2_Llb_iss
	s_cmp_gt_u32 s5, 4
	s_cbranch_scc1 .Llbt3_Llb_iss
	s_cmp_gt_u32 s5, 2
	s_cbranch_scc1 .Llbt4_Llb_iss
	s_cmp_gt_u32 s5, 1
	s_cbranch_scc1 .Llbt5_Llb_iss
	s_branch .Llb_iss_0
.Llbt5_Llb_iss:
	s_branch .Llb_iss_1
.Llbt4_Llb_iss:
	s_cmp_gt_u32 s5, 3
	s_cbranch_scc1 .Llbt6_Llb_iss
	s_branch .Llb_iss_2

.Llbt3_Llb_iss:
	s_cmp_gt_u32 s5, 6
	s_cbranch_scc1 .Llbt7_Llb_iss
	s_cmp_gt_u32 s5, 5
	s_cbranch_scc1 .Llbt8_Llb_iss
	s_branch .Llb_iss_4

.Llbt7_Llb_iss:
	s_cmp_gt_u32 s5, 7
	s_cbranch_scc1 .Llbt9_Llb_iss
	s_branch .Llb_iss_6

.Llbt2_Llb_iss:
	s_cmp_gt_u32 s5, 12
	s_cbranch_scc1 .Llbt10_Llb_iss
	s_cmp_gt_u32 s5, 10
	s_cbranch_scc1 .Llbt11_Llb_iss
	s_cmp_gt_u32 s5, 9
	s_cbranch_scc1 .Llbt12_Llb_iss
	s_branch .Llb_iss_8

.Llbt11_Llb_iss:
	s_cmp_gt_u32 s5, 11
	s_cbranch_scc1 .Llbt13_Llb_iss
	s_branch .Llb_iss_10

.Llbt10_Llb_iss:
	s_cmp_gt_u32 s5, 14
	s_cbranch_scc1 .Llbt14_Llb_iss
	s_cmp_gt_u32 s5, 13
	s_cbranch_scc1 .Llbt15_Llb_iss
	s_branch .Llb_iss_12

.Llbt14_Llb_iss:
	s_cmp_gt_u32 s5, 15
	s_cbranch_scc1 .Llbt16_Llb_iss
	s_branch .Llb_iss_14

.Llbt1_Llb_iss:
	s_cmp_gt_u32 s5, 24
	s_cbranch_scc1 .Llbt17_Llb_iss
	s_cmp_gt_u32 s5, 20
	s_cbranch_scc1 .Llbt18_Llb_iss
	s_cmp_gt_u32 s5, 18
	s_cbranch_scc1 .Llbt19_Llb_iss
	s_cmp_gt_u32 s5, 17
	s_cbranch_scc1 .Llbt20_Llb_iss
	s_branch .Llb_iss_16

.Llbt19_Llb_iss:
	s_cmp_gt_u32 s5, 19
	s_cbranch_scc1 .Llbt21_Llb_iss
	s_branch .Llb_iss_18

.Llbt18_Llb_iss:
	s_cmp_gt_u32 s5, 22
	s_cbranch_scc1 .Llbt22_Llb_iss
	s_cmp_gt_u32 s5, 21
	s_cbranch_scc1 .Llbt23_Llb_iss
	s_branch .Llb_iss_20

.Llbt22_Llb_iss:
	s_cmp_gt_u32 s5, 23
	s_cbranch_scc1 .Llbt24_Llb_iss
	s_branch .Llb_iss_22

.Llbt17_Llb_iss:
	s_cmp_gt_u32 s5, 28
	s_cbranch_scc1 .Llbt25_Llb_iss
	s_cmp_gt_u32 s5, 26
	s_cbranch_scc1 .Llbt26_Llb_iss
	s_cmp_gt_u32 s5, 25
	s_cbranch_scc1 .Llbt27_Llb_iss
	s_branch .Llb_iss_24

.Llbt26_Llb_iss:
	s_cmp_gt_u32 s5, 27
	s_cbranch_scc1 .Llbt28_Llb_iss
	s_branch .Llb_iss_26

.Llbt25_Llb_iss:
	s_cmp_gt_u32 s5, 30
	s_cbranch_scc1 .Llbt29_Llb_iss
	s_cmp_gt_u32 s5, 29
	s_cbranch_scc1 .Llbt30_Llb_iss
	s_branch .Llb_iss_28

.Llb_iss_30:
	global_load_dwordx4 v[240:243], v192, s[2:3]
	global_load_dwordx4 v[244:247], v134, s[2:3]
	s_add_u32 s2, s2, 0x4000
	s_addc_u32 s3, s3, 0
.Llb_iss_29:
	global_load_dwordx4 v[232:235], v192, s[2:3]
	global_load_dwordx4 v[236:239], v134, s[2:3]
	s_add_u32 s2, s2, 0x4000
	s_addc_u32 s3, s3, 0
.Llb_iss_28:
	global_load_dwordx4 v[214:217], v192, s[2:3]
	global_load_dwordx4 v[218:221], v134, s[2:3]
	s_add_u32 s2, s2, 0x4000
	s_addc_u32 s3, s3, 0
.Llb_iss_27:
	global_load_dwordx4 v[206:209], v192, s[2:3]
	global_load_dwordx4 v[210:213], v134, s[2:3]
	s_add_u32 s2, s2, 0x4000
	s_addc_u32 s3, s3, 0
.Llb_iss_26:
	global_load_dwordx4 v[194:197], v192, s[2:3]
	global_load_dwordx4 v[198:201], v134, s[2:3]
	s_add_u32 s2, s2, 0x4000
	s_addc_u32 s3, s3, 0
.Llb_iss_25:
	global_load_dwordx4 v[180:183], v192, s[2:3]
	global_load_dwordx4 v[184:187], v134, s[2:3]
	s_add_u32 s2, s2, 0x4000
	s_addc_u32 s3, s3, 0
.Llb_iss_24:
	global_load_dwordx4 v[172:175], v192, s[2:3]
	global_load_dwordx4 v[176:179], v134, s[2:3]
	s_add_u32 s2, s2, 0x4000
	s_addc_u32 s3, s3, 0
.Llb_iss_23:
	global_load_dwordx4 v[164:167], v192, s[2:3]
	global_load_dwordx4 v[168:171], v134, s[2:3]
	s_add_u32 s2, s2, 0x4000
	s_addc_u32 s3, s3, 0
.Llb_iss_22:
	global_load_dwordx4 v[156:159], v192, s[2:3]
	global_load_dwordx4 v[160:163], v134, s[2:3]
	s_add_u32 s2, s2, 0x4000
	s_addc_u32 s3, s3, 0
.Llb_iss_21:
	global_load_dwordx4 v[104:107], v192, s[2:3]
	global_load_dwordx4 v[108:111], v134, s[2:3]
	s_add_u32 s2, s2, 0x4000
	s_addc_u32 s3, s3, 0
.Llb_iss_20:
	global_load_dwordx4 v[96:99], v192, s[2:3]
	global_load_dwordx4 v[100:103], v134, s[2:3]
	s_add_u32 s2, s2, 0x4000
	s_addc_u32 s3, s3, 0
.Llb_iss_19:
	global_load_dwordx4 v[88:91], v192, s[2:3]
	global_load_dwordx4 v[92:95], v134, s[2:3]
	s_add_u32 s2, s2, 0x4000
	s_addc_u32 s3, s3, 0
.Llb_iss_18:
	global_load_dwordx4 v[40:43], v192, s[2:3]
	global_load_dwordx4 v[44:47], v134, s[2:3]
	s_add_u32 s2, s2, 0x4000
	s_addc_u32 s3, s3, 0
.Llb_iss_17:
	global_load_dwordx4 v[32:35], v192, s[2:3]
	global_load_dwordx4 v[36:39], v134, s[2:3]
	s_add_u32 s2, s2, 0x4000
	s_addc_u32 s3, s3, 0
.Llb_iss_16:
	global_load_dwordx4 v[24:27], v192, s[2:3]
	global_load_dwordx4 v[28:31], v134, s[2:3]
	s_add_u32 s2, s2, 0x4000
	s_addc_u32 s3, s3, 0
.Llb_iss_15:
	global_load_dwordx4 v[188:191], v192, s[2:3]
	global_load_dwordx4 v[222:225], v134, s[2:3]
	s_add_u32 s2, s2, 0x4000
	s_addc_u32 s3, s3, 0
.Llb_iss_14:
	s_cmp_gt_i32 s6, 14
	s_cbranch_scc1 .Llb_disp
	global_load_dwordx4 v[240:243], v192, s[2:3]
	global_load_dwordx4 v[244:247], v134, s[2:3]
	s_add_u32 s2, s2, 0x4000
	s_addc_u32 s3, s3, 0
.Llb_iss_13:
	s_cmp_gt_i32 s6, 13
	s_cbranch_scc1 .Llb_disp
	global_load_dwordx4 v[232:235], v192, s[2:3]
	global_load_dwordx4 v[236:239], v134, s[2:3]
	s_add_u32 s2, s2, 0x4000
	s_addc_u32 s3, s3, 0
.Llb_iss_12:
	s_cmp_gt_i32 s6, 12
	s_cbranch_scc1 .Llb_disp
	global_load_dwordx4 v[214:217], v192, s[2:3]
	global_load_dwordx4 v[218:221], v134, s[2:3]
	s_add_u32 s2, s2, 0x4000
	s_addc_u32 s3, s3, 0
.Llb_iss_11:
	s_cmp_gt_i32 s6, 11
	s_cbranch_scc1 .Llb_disp
	global_load_dwordx4 v[206:209], v192, s[2:3]
	global_load_dwordx4 v[210:213], v134, s[2:3]
	s_add_u32 s2, s2, 0x4000
	s_addc_u32 s3, s3, 0
.Llb_iss_10:
	s_cmp_gt_i32 s6, 10
	s_cbranch_scc1 .Llb_disp
	global_load_dwordx4 v[194:197], v192, s[2:3]
	global_load_dwordx4 v[198:201], v134, s[2:3]
	s_add_u32 s2, s2, 0x4000
	s_addc_u32 s3, s3, 0
.Llb_iss_9:
	s_cmp_gt_i32 s6, 9
	s_cbranch_scc1 .Llb_disp
	global_load_dwordx4 v[180:183], v192, s[2:3]
	global_load_dwordx4 v[184:187], v134, s[2:3]
	s_add_u32 s2, s2, 0x4000
	s_addc_u32 s3, s3, 0
.Llb_iss_8:
	s_cmp_gt_i32 s6, 8
	s_cbranch_scc1 .Llb_disp
	global_load_dwordx4 v[172:175], v192, s[2:3]
	global_load_dwordx4 v[176:179], v134, s[2:3]
	s_add_u32 s2, s2, 0x4000
	s_addc_u32 s3, s3, 0
.Llb_iss_7:
	s_cmp_gt_i32 s6, 7
	s_cbranch_scc1 .Llb_disp
	global_load_dwordx4 v[164:167], v192, s[2:3]
	global_load_dwordx4 v[168:171], v134, s[2:3]
	s_add_u32 s2, s2, 0x4000
	s_addc_u32 s3, s3, 0
.Llb_iss_6:
	s_cmp_gt_i32 s6, 6
	s_cbranch_scc1 .Llb_disp
	global_load_dwordx4 v[156:159], v192, s[2:3]
	global_load_dwordx4 v[160:163], v134, s[2:3]
	s_add_u32 s2, s2, 0x4000
	s_addc_u32 s3, s3, 0
.Llb_iss_5:
	s_cmp_gt_i32 s6, 5
	s_cbranch_scc1 .Llb_disp
	global_load_dwordx4 v[104:107], v192, s[2:3]
	global_load_dwordx4 v[108:111], v134, s[2:3]
	s_add_u32 s2, s2, 0x4000
	s_addc_u32 s3, s3, 0
.Llb_iss_4:
	s_cmp_gt_i32 s6, 4
	s_cbranch_scc1 .Llb_disp
	global_load_dwordx4 v[96:99], v192, s[2:3]
	global_load_dwordx4 v[100:103], v134, s[2:3]
	s_add_u32 s2, s2, 0x4000
	s_addc_u32 s3, s3, 0
.Llb_iss_3:
	s_cmp_gt_i32 s6, 3
	s_cbranch_scc1 .Llb_disp
	global_load_dwordx4 v[88:91], v192, s[2:3]
	global_load_dwordx4 v[92:95], v134, s[2:3]
	s_add_u32 s2, s2, 0x4000
	s_addc_u32 s3, s3, 0
.Llb_iss_2:
	s_cmp_gt_i32 s6, 2
	s_cbranch_scc1 .Llb_disp
	global_load_dwordx4 v[40:43], v192, s[2:3]
	global_load_dwordx4 v[44:47], v134, s[2:3]
	s_add_u32 s2, s2, 0x4000
	s_addc_u32 s3, s3, 0
.Llb_iss_1:
	s_cmp_gt_i32 s6, 1
	s_cbranch_scc1 .Llb_disp
	global_load_dwordx4 v[32:35], v192, s[2:3]
	global_load_dwordx4 v[36:39], v134, s[2:3]
	s_add_u32 s2, s2, 0x4000
	s_addc_u32 s3, s3, 0
.Llb_iss_0:
	s_cmp_gt_i32 s6, 0
	s_cbranch_scc1 .Llb_disp
	global_load_dwordx4 v[24:27], v192, s[2:3]
	global_load_dwordx4 v[28:31], v134, s[2:3]
	s_add_u32 s2, s2, 0x4000
	s_addc_u32 s3, s3, 0
.Llb_disp:
	s_cmp_gt_u32 s5, 16
	s_cbranch_scc1 .Llbt31_Llb_proc
	s_cmp_gt_u32 s5, 8
	s_cbranch_scc1 .Llbt32_Llb_proc
	s_cmp_gt_u32 s5, 4
	s_cbranch_scc1 .Llbt33_Llb_proc
	s_cmp_gt_u32 s5, 2
	s_cbranch_scc1 .Llbt34_Llb_proc
	s_cmp_gt_u32 s5, 1
	s_cbranch_scc1 .Llbt35_Llb_proc
	s_branch .Llb_proc_0

.Llb_proc_30:
	s_waitcnt vmcnt(30)
	v_and_b32_e32 v148, 0xffff0000, v240
	v_lshlrev_b32_e32 v149, 16, v240
	v_and_b32_e32 v146, 0xffff0000, v241
	v_lshlrev_b32_e32 v147, 16, v241
	v_and_b32_e32 v202, 0xffff0000, v242
	v_lshlrev_b32_e32 v203, 16, v242
	v_pk_fma_f32 v[136:137], v[124:125], v[136:137], v[148:149]
	v_and_b32_e32 v248, 0xffff0000, v243
	v_lshlrev_b32_e32 v249, 16, v243
	v_pk_fma_f32 v[138:139], v[124:125], v[138:139], v[146:147]
	v_and_b32_e32 v148, 0xffff0000, v244
	v_lshlrev_b32_e32 v149, 16, v244
	v_pk_fma_f32 v[140:141], v[124:125], v[140:141], v[202:203]
	v_and_b32_e32 v146, 0xffff0000, v245
	v_lshlrev_b32_e32 v147, 16, v245
	v_pk_fma_f32 v[142:143], v[124:125], v[142:143], v[248:249]
	v_and_b32_e32 v202, 0xffff0000, v246
	v_lshlrev_b32_e32 v203, 16, v246
	v_pk_fma_f32 v[144:145], v[124:125], v[144:145], v[148:149]
	v_and_b32_e32 v248, 0xffff0000, v247
	v_lshlrev_b32_e32 v249, 16, v247
	v_pk_fma_f32 v[132:133], v[124:125], v[132:133], v[146:147]
	v_pk_fma_f32 v[130:131], v[124:125], v[130:131], v[202:203]
	v_pk_fma_f32 v[128:129], v[124:125], v[128:129], v[248:249]
	global_load_dwordx4 v[240:243], v192, s[2:3]
	global_load_dwordx4 v[244:247], v134, s[2:3]
	s_add_u32 s2, s2, 0x4000
	s_addc_u32 s3, s3, 0
.Llb_proc_29:
	s_waitcnt vmcnt(30)
	v_and_b32_e32 v148, 0xffff0000, v232
	v_lshlrev_b32_e32 v149, 16, v232
	v_and_b32_e32 v146, 0xffff0000, v233
	v_lshlrev_b32_e32 v147, 16, v233
	v_and_b32_e32 v202, 0xffff0000, v234
	v_lshlrev_b32_e32 v203, 16, v234
	v_pk_fma_f32 v[136:137], v[124:125], v[136:137], v[148:149]
	v_and_b32_e32 v248, 0xffff0000, v235
	v_lshlrev_b32_e32 v249, 16, v235
	v_pk_fma_f32 v[138:139], v[124:125], v[138:139], v[146:147]
	v_and_b32_e32 v148, 0xffff0000, v236
	v_lshlrev_b32_e32 v149, 16, v236
	v_pk_fma_f32 v[140:141], v[124:125], v[140:141], v[202:203]
	v_and_b32_e32 v146, 0xffff0000, v237
	v_lshlrev_b32_e32 v147, 16, v237
	v_pk_fma_f32 v[142:143], v[124:125], v[142:143], v[248:249]
	v_and_b32_e32 v202, 0xffff0000, v238
	v_lshlrev_b32_e32 v203, 16, v238
	v_pk_fma_f32 v[144:145], v[124:125], v[144:145], v[148:149]
	v_and_b32_e32 v248, 0xffff0000, v239
	v_lshlrev_b32_e32 v249, 16, v239
	v_pk_fma_f32 v[132:133], v[124:125], v[132:133], v[146:147]
	v_pk_fma_f32 v[130:131], v[124:125], v[130:131], v[202:203]
	v_pk_fma_f32 v[128:129], v[124:125], v[128:129], v[248:249]
	global_load_dwordx4 v[232:235], v192, s[2:3]
	global_load_dwordx4 v[236:239], v134, s[2:3]
	s_add_u32 s2, s2, 0x4000
	s_addc_u32 s3, s3, 0
.Llb_proc_28:
	s_waitcnt vmcnt(30)
	v_and_b32_e32 v148, 0xffff0000, v214
	v_lshlrev_b32_e32 v149, 16, v214
	v_and_b32_e32 v146, 0xffff0000, v215
	v_lshlrev_b32_e32 v147, 16, v215
	v_and_b32_e32 v202, 0xffff0000, v216
	v_lshlrev_b32_e32 v203, 16, v216
	v_pk_fma_f32 v[136:137], v[124:125], v[136:137], v[148:149]
	v_and_b32_e32 v248, 0xffff0000, v217
	v_lshlrev_b32_e32 v249, 16, v217
	v_pk_fma_f32 v[138:139], v[124:125], v[138:139], v[146:147]
	v_and_b32_e32 v148, 0xffff0000, v218
	v_lshlrev_b32_e32 v149, 16, v218
	v_pk_fma_f32 v[140:141], v[124:125], v[140:141], v[202:203]
	v_and_b32_e32 v146, 0xffff0000, v219
	v_lshlrev_b32_e32 v147, 16, v219
	v_pk_fma_f32 v[142:143], v[124:125], v[142:143], v[248:249]
	v_and_b32_e32 v202, 0xffff0000, v220
	v_lshlrev_b32_e32 v203, 16, v220
	v_pk_fma_f32 v[144:145], v[124:125], v[144:145], v[148:149]
	v_and_b32_e32 v248, 0xffff0000, v221
	v_lshlrev_b32_e32 v249, 16, v221
	v_pk_fma_f32 v[132:133], v[124:125], v[132:133], v[146:147]
	v_pk_fma_f32 v[130:131], v[124:125], v[130:131], v[202:203]
	v_pk_fma_f32 v[128:129], v[124:125], v[128:129], v[248:249]
	global_load_dwordx4 v[214:217], v192, s[2:3]
	global_load_dwordx4 v[218:221], v134, s[2:3]
	s_add_u32 s2, s2, 0x4000
	s_addc_u32 s3, s3, 0
.Llb_proc_27:
	s_waitcnt vmcnt(30)
	v_and_b32_e32 v148, 0xffff0000, v206
	v_lshlrev_b32_e32 v149, 16, v206
	v_and_b32_e32 v146, 0xffff0000, v207
	v_lshlrev_b32_e32 v147, 16, v207
	v_and_b32_e32 v202, 0xffff0000, v208
	v_lshlrev_b32_e32 v203, 16, v208
	v_pk_fma_f32 v[136:137], v[124:125], v[136:137], v[148:149]
	v_and_b32_e32 v248, 0xffff0000, v209
	v_lshlrev_b32_e32 v249, 16, v209
	v_pk_fma_f32 v[138:139], v[124:125], v[138:139], v[146:147]
	v_and_b32_e32 v148, 0xffff0000, v210
	v_lshlrev_b32_e32 v149, 16, v210
	v_pk_fma_f32 v[140:141], v[124:125], v[140:141], v[202:203]
	v_and_b32_e32 v146, 0xffff0000, v211
	v_lshlrev_b32_e32 v147, 16, v211
	v_pk_fma_f32 v[142:143], v[124:125], v[142:143], v[248:249]
	v_and_b32_e32 v202, 0xffff0000, v212
	v_lshlrev_b32_e32 v203, 16, v212
	v_pk_fma_f32 v[144:145], v[124:125], v[144:145], v[148:149]
	v_and_b32_e32 v248, 0xffff0000, v213
	v_lshlrev_b32_e32 v249, 16, v213
	v_pk_fma_f32 v[132:133], v[124:125], v[132:133], v[146:147]
	v_pk_fma_f32 v[130:131], v[124:125], v[130:131], v[202:203]
	v_pk_fma_f32 v[128:129], v[124:125], v[128:129], v[248:249]
	global_load_dwordx4 v[206:209], v192, s[2:3]
	global_load_dwordx4 v[210:213], v134, s[2:3]
	s_add_u32 s2, s2, 0x4000
	s_addc_u32 s3, s3, 0
.Llb_proc_26:
	s_waitcnt vmcnt(30)
	v_and_b32_e32 v148, 0xffff0000, v194
	v_lshlrev_b32_e32 v149, 16, v194
	v_and_b32_e32 v146, 0xffff0000, v195
	v_lshlrev_b32_e32 v147, 16, v195
	v_and_b32_e32 v202, 0xffff0000, v196
	v_lshlrev_b32_e32 v203, 16, v196
	v_pk_fma_f32 v[136:137], v[124:125], v[136:137], v[148:149]
	v_and_b32_e32 v248, 0xffff0000, v197
	v_lshlrev_b32_e32 v249, 16, v197
	v_pk_fma_f32 v[138:139], v[124:125], v[138:139], v[146:147]
	v_and_b32_e32 v148, 0xffff0000, v198
	v_lshlrev_b32_e32 v149, 16, v198
	v_pk_fma_f32 v[140:141], v[124:125], v[140:141], v[202:203]
	v_and_b32_e32 v146, 0xffff0000, v199
	v_lshlrev_b32_e32 v147, 16, v199
	v_pk_fma_f32 v[142:143], v[124:125], v[142:143], v[248:249]
	v_and_b32_e32 v202, 0xffff0000, v200
	v_lshlrev_b32_e32 v203, 16, v200
	v_pk_fma_f32 v[144:145], v[124:125], v[144:145], v[148:149]
	v_and_b32_e32 v248, 0xffff0000, v201
	v_lshlrev_b32_e32 v249, 16, v201
	v_pk_fma_f32 v[132:133], v[124:125], v[132:133], v[146:147]
	v_pk_fma_f32 v[130:131], v[124:125], v[130:131], v[202:203]
	v_pk_fma_f32 v[128:129], v[124:125], v[128:129], v[248:249]
	global_load_dwordx4 v[194:197], v192, s[2:3]
	global_load_dwordx4 v[198:201], v134, s[2:3]
	s_add_u32 s2, s2, 0x4000
	s_addc_u32 s3, s3, 0
.Llb_proc_25:
	s_waitcnt vmcnt(30)
	v_and_b32_e32 v148, 0xffff0000, v180
	v_lshlrev_b32_e32 v149, 16, v180
	v_and_b32_e32 v146, 0xffff0000, v181
	v_lshlrev_b32_e32 v147, 16, v181
	v_and_b32_e32 v202, 0xffff0000, v182
	v_lshlrev_b32_e32 v203, 16, v182
	v_pk_fma_f32 v[136:137], v[124:125], v[136:137], v[148:149]
	v_and_b32_e32 v248, 0xffff0000, v183
	v_lshlrev_b32_e32 v249, 16, v183
	v_pk_fma_f32 v[138:139], v[124:125], v[138:139], v[146:147]
	v_and_b32_e32 v148, 0xffff0000, v184
	v_lshlrev_b32_e32 v149, 16, v184
	v_pk_fma_f32 v[140:141], v[124:125], v[140:141], v[202:203]
	v_and_b32_e32 v146, 0xffff0000, v185
	v_lshlrev_b32_e32 v147, 16, v185
	v_pk_fma_f32 v[142:143], v[124:125], v[142:143], v[248:249]
	v_and_b32_e32 v202, 0xffff0000, v186
	v_lshlrev_b32_e32 v203, 16, v186
	v_pk_fma_f32 v[144:145], v[124:125], v[144:145], v[148:149]
	v_and_b32_e32 v248, 0xffff0000, v187
	v_lshlrev_b32_e32 v249, 16, v187
	v_pk_fma_f32 v[132:133], v[124:125], v[132:133], v[146:147]
	v_pk_fma_f32 v[130:131], v[124:125], v[130:131], v[202:203]
	v_pk_fma_f32 v[128:129], v[124:125], v[128:129], v[248:249]
	global_load_dwordx4 v[180:183], v192, s[2:3]
	global_load_dwordx4 v[184:187], v134, s[2:3]
	s_add_u32 s2, s2, 0x4000
	s_addc_u32 s3, s3, 0
.Llb_proc_24:
	s_waitcnt vmcnt(30)
	v_and_b32_e32 v148, 0xffff0000, v172
	v_lshlrev_b32_e32 v149, 16, v172
	v_and_b32_e32 v146, 0xffff0000, v173
	v_lshlrev_b32_e32 v147, 16, v173
	v_and_b32_e32 v202, 0xffff0000, v174
	v_lshlrev_b32_e32 v203, 16, v174
	v_pk_fma_f32 v[136:137], v[124:125], v[136:137], v[148:149]
	v_and_b32_e32 v248, 0xffff0000, v175
	v_lshlrev_b32_e32 v249, 16, v175
	v_pk_fma_f32 v[138:139], v[124:125], v[138:139], v[146:147]
	v_and_b32_e32 v148, 0xffff0000, v176
	v_lshlrev_b32_e32 v149, 16, v176
	v_pk_fma_f32 v[140:141], v[124:125], v[140:141], v[202:203]
	v_and_b32_e32 v146, 0xffff0000, v177
	v_lshlrev_b32_e32 v147, 16, v177
	v_pk_fma_f32 v[142:143], v[124:125], v[142:143], v[248:249]
	v_and_b32_e32 v202, 0xffff0000, v178
	v_lshlrev_b32_e32 v203, 16, v178
	v_pk_fma_f32 v[144:145], v[124:125], v[144:145], v[148:149]
	v_and_b32_e32 v248, 0xffff0000, v179
	v_lshlrev_b32_e32 v249, 16, v179
	v_pk_fma_f32 v[132:133], v[124:125], v[132:133], v[146:147]
	v_pk_fma_f32 v[130:131], v[124:125], v[130:131], v[202:203]
	v_pk_fma_f32 v[128:129], v[124:125], v[128:129], v[248:249]
	global_load_dwordx4 v[172:175], v192, s[2:3]
	global_load_dwordx4 v[176:179], v134, s[2:3]
	s_add_u32 s2, s2, 0x4000
	s_addc_u32 s3, s3, 0
.Llb_proc_23:
	s_waitcnt vmcnt(30)
	v_and_b32_e32 v148, 0xffff0000, v164
	v_lshlrev_b32_e32 v149, 16, v164
	v_and_b32_e32 v146, 0xffff0000, v165
	v_lshlrev_b32_e32 v147, 16, v165
	v_and_b32_e32 v202, 0xffff0000, v166
	v_lshlrev_b32_e32 v203, 16, v166
	v_pk_fma_f32 v[136:137], v[124:125], v[136:137], v[148:149]
	v_and_b32_e32 v248, 0xffff0000, v167
	v_lshlrev_b32_e32 v249, 16, v167
	v_pk_fma_f32 v[138:139], v[124:125], v[138:139], v[146:147]
	v_and_b32_e32 v148, 0xffff0000, v168
	v_lshlrev_b32_e32 v149, 16, v168
	v_pk_fma_f32 v[140:141], v[124:125], v[140:141], v[202:203]
	v_and_b32_e32 v146, 0xffff0000, v169
	v_lshlrev_b32_e32 v147, 16, v169
	v_pk_fma_f32 v[142:143], v[124:125], v[142:143], v[248:249]
	v_and_b32_e32 v202, 0xffff0000, v170
	v_lshlrev_b32_e32 v203, 16, v170
	v_pk_fma_f32 v[144:145], v[124:125], v[144:145], v[148:149]
	v_and_b32_e32 v248, 0xffff0000, v171
	v_lshlrev_b32_e32 v249, 16, v171
	v_pk_fma_f32 v[132:133], v[124:125], v[132:133], v[146:147]
	v_pk_fma_f32 v[130:131], v[124:125], v[130:131], v[202:203]
	v_pk_fma_f32 v[128:129], v[124:125], v[128:129], v[248:249]
	global_load_dwordx4 v[164:167], v192, s[2:3]
	global_load_dwordx4 v[168:171], v134, s[2:3]
	s_add_u32 s2, s2, 0x4000
	s_addc_u32 s3, s3, 0
.Llb_proc_22:
	s_waitcnt vmcnt(30)
	v_and_b32_e32 v148, 0xffff0000, v156
	v_lshlrev_b32_e32 v149, 16, v156
	v_and_b32_e32 v146, 0xffff0000, v157
	v_lshlrev_b32_e32 v147, 16, v157
	v_and_b32_e32 v202, 0xffff0000, v158
	v_lshlrev_b32_e32 v203, 16, v158
	v_pk_fma_f32 v[136:137], v[124:125], v[136:137], v[148:149]
	v_and_b32_e32 v248, 0xffff0000, v159
	v_lshlrev_b32_e32 v249, 16, v159
	v_pk_fma_f32 v[138:139], v[124:125], v[138:139], v[146:147]
	v_and_b32_e32 v148, 0xffff0000, v160
	v_lshlrev_b32_e32 v149, 16, v160
	v_pk_fma_f32 v[140:141], v[124:125], v[140:141], v[202:203]
	v_and_b32_e32 v146, 0xffff0000, v161
	v_lshlrev_b32_e32 v147, 16, v161
	v_pk_fma_f32 v[142:143], v[124:125], v[142:143], v[248:249]
	v_and_b32_e32 v202, 0xffff0000, v162
	v_lshlrev_b32_e32 v203, 16, v162
	v_pk_fma_f32 v[144:145], v[124:125], v[144:145], v[148:149]
	v_and_b32_e32 v248, 0xffff0000, v163
	v_lshlrev_b32_e32 v249, 16, v163
	v_pk_fma_f32 v[132:133], v[124:125], v[132:133], v[146:147]
	v_pk_fma_f32 v[130:131], v[124:125], v[130:131], v[202:203]
	v_pk_fma_f32 v[128:129], v[124:125], v[128:129], v[248:249]
	global_load_dwordx4 v[156:159], v192, s[2:3]
	global_load_dwordx4 v[160:163], v134, s[2:3]
	s_add_u32 s2, s2, 0x4000
	s_addc_u32 s3, s3, 0
.Llb_proc_21:
	s_waitcnt vmcnt(30)
	v_and_b32_e32 v148, 0xffff0000, v104
	v_lshlrev_b32_e32 v149, 16, v104
	v_and_b32_e32 v146, 0xffff0000, v105
	v_lshlrev_b32_e32 v147, 16, v105
	v_and_b32_e32 v202, 0xffff0000, v106
	v_lshlrev_b32_e32 v203, 16, v106
	v_pk_fma_f32 v[136:137], v[124:125], v[136:137], v[148:149]
	v_and_b32_e32 v248, 0xffff0000, v107
	v_lshlrev_b32_e32 v249, 16, v107
	v_pk_fma_f32 v[138:139], v[124:125], v[138:139], v[146:147]
	v_and_b32_e32 v148, 0xffff0000, v108
	v_lshlrev_b32_e32 v149, 16, v108
	v_pk_fma_f32 v[140:141], v[124:125], v[140:141], v[202:203]
	v_and_b32_e32 v146, 0xffff0000, v109
	v_lshlrev_b32_e32 v147, 16, v109
	v_pk_fma_f32 v[142:143], v[124:125], v[142:143], v[248:249]
	v_and_b32_e32 v202, 0xffff0000, v110
	v_lshlrev_b32_e32 v203, 16, v110
	v_pk_fma_f32 v[144:145], v[124:125], v[144:145], v[148:149]
	v_and_b32_e32 v248, 0xffff0000, v111
	v_lshlrev_b32_e32 v249, 16, v111
	v_pk_fma_f32 v[132:133], v[124:125], v[132:133], v[146:147]
	v_pk_fma_f32 v[130:131], v[124:125], v[130:131], v[202:203]
	v_pk_fma_f32 v[128:129], v[124:125], v[128:129], v[248:249]
	global_load_dwordx4 v[104:107], v192, s[2:3]
	global_load_dwordx4 v[108:111], v134, s[2:3]
	s_add_u32 s2, s2, 0x4000
	s_addc_u32 s3, s3, 0
.Llb_proc_20:
	s_waitcnt vmcnt(30)
	v_and_b32_e32 v148, 0xffff0000, v96
	v_lshlrev_b32_e32 v149, 16, v96
	v_and_b32_e32 v146, 0xffff0000, v97
	v_lshlrev_b32_e32 v147, 16, v97
	v_and_b32_e32 v202, 0xffff0000, v98
	v_lshlrev_b32_e32 v203, 16, v98
	v_pk_fma_f32 v[136:137], v[124:125], v[136:137], v[148:149]
	v_and_b32_e32 v248, 0xffff0000, v99
	v_lshlrev_b32_e32 v249, 16, v99
	v_pk_fma_f32 v[138:139], v[124:125], v[138:139], v[146:147]
	v_and_b32_e32 v148, 0xffff0000, v100
	v_lshlrev_b32_e32 v149, 16, v100
	v_pk_fma_f32 v[140:141], v[124:125], v[140:141], v[202:203]
	v_and_b32_e32 v146, 0xffff0000, v101
	v_lshlrev_b32_e32 v147, 16, v101
	v_pk_fma_f32 v[142:143], v[124:125], v[142:143], v[248:249]
	v_and_b32_e32 v202, 0xffff0000, v102
	v_lshlrev_b32_e32 v203, 16, v102
	v_pk_fma_f32 v[144:145], v[124:125], v[144:145], v[148:149]
	v_and_b32_e32 v248, 0xffff0000, v103
	v_lshlrev_b32_e32 v249, 16, v103
	v_pk_fma_f32 v[132:133], v[124:125], v[132:133], v[146:147]
	v_pk_fma_f32 v[130:131], v[124:125], v[130:131], v[202:203]
	v_pk_fma_f32 v[128:129], v[124:125], v[128:129], v[248:249]
	global_load_dwordx4 v[96:99], v192, s[2:3]
	global_load_dwordx4 v[100:103], v134, s[2:3]
	s_add_u32 s2, s2, 0x4000
	s_addc_u32 s3, s3, 0
.Llb_proc_19:
	s_waitcnt vmcnt(30)
	v_and_b32_e32 v148, 0xffff0000, v88
	v_lshlrev_b32_e32 v149, 16, v88
	v_and_b32_e32 v146, 0xffff0000, v89
	v_lshlrev_b32_e32 v147, 16, v89
	v_and_b32_e32 v202, 0xffff0000, v90
	v_lshlrev_b32_e32 v203, 16, v90
	v_pk_fma_f32 v[136:137], v[124:125], v[136:137], v[148:149]
	v_and_b32_e32 v248, 0xffff0000, v91
	v_lshlrev_b32_e32 v249, 16, v91
	v_pk_fma_f32 v[138:139], v[124:125], v[138:139], v[146:147]
	v_and_b32_e32 v148, 0xffff0000, v92
	v_lshlrev_b32_e32 v149, 16, v92
	v_pk_fma_f32 v[140:141], v[124:125], v[140:141], v[202:203]
	v_and_b32_e32 v146, 0xffff0000, v93
	v_lshlrev_b32_e32 v147, 16, v93
	v_pk_fma_f32 v[142:143], v[124:125], v[142:143], v[248:249]
	v_and_b32_e32 v202, 0xffff0000, v94
	v_lshlrev_b32_e32 v203, 16, v94
	v_pk_fma_f32 v[144:145], v[124:125], v[144:145], v[148:149]
	v_and_b32_e32 v248, 0xffff0000, v95
	v_lshlrev_b32_e32 v249, 16, v95
	v_pk_fma_f32 v[132:133], v[124:125], v[132:133], v[146:147]
	v_pk_fma_f32 v[130:131], v[124:125], v[130:131], v[202:203]
	v_pk_fma_f32 v[128:129], v[124:125], v[128:129], v[248:249]
	global_load_dwordx4 v[88:91], v192, s[2:3]
	global_load_dwordx4 v[92:95], v134, s[2:3]
	s_add_u32 s2, s2, 0x4000
	s_addc_u32 s3, s3, 0
.Llb_proc_18:
	s_waitcnt vmcnt(30)
	v_and_b32_e32 v148, 0xffff0000, v40
	v_lshlrev_b32_e32 v149, 16, v40
	v_and_b32_e32 v146, 0xffff0000, v41
	v_lshlrev_b32_e32 v147, 16, v41
	v_and_b32_e32 v202, 0xffff0000, v42
	v_lshlrev_b32_e32 v203, 16, v42
	v_pk_fma_f32 v[136:137], v[124:125], v[136:137], v[148:149]
	v_and_b32_e32 v248, 0xffff0000, v43
	v_lshlrev_b32_e32 v249, 16, v43
	v_pk_fma_f32 v[138:139], v[124:125], v[138:139], v[146:147]
	v_and_b32_e32 v148, 0xffff0000, v44
	v_lshlrev_b32_e32 v149, 16, v44
	v_pk_fma_f32 v[140:141], v[124:125], v[140:141], v[202:203]
	v_and_b32_e32 v146, 0xffff0000, v45
	v_lshlrev_b32_e32 v147, 16, v45
	v_pk_fma_f32 v[142:143], v[124:125], v[142:143], v[248:249]
	v_and_b32_e32 v202, 0xffff0000, v46
	v_lshlrev_b32_e32 v203, 16, v46
	v_pk_fma_f32 v[144:145], v[124:125], v[144:145], v[148:149]
	v_and_b32_e32 v248, 0xffff0000, v47
	v_lshlrev_b32_e32 v249, 16, v47
	v_pk_fma_f32 v[132:133], v[124:125], v[132:133], v[146:147]
	v_pk_fma_f32 v[130:131], v[124:125], v[130:131], v[202:203]
	v_pk_fma_f32 v[128:129], v[124:125], v[128:129], v[248:249]
	global_load_dwordx4 v[40:43], v192, s[2:3]
	global_load_dwordx4 v[44:47], v134, s[2:3]
	s_add_u32 s2, s2, 0x4000
	s_addc_u32 s3, s3, 0
.Llb_proc_17:
	s_waitcnt vmcnt(30)
	v_and_b32_e32 v148, 0xffff0000, v32
	v_lshlrev_b32_e32 v149, 16, v32
	v_and_b32_e32 v146, 0xffff0000, v33
	v_lshlrev_b32_e32 v147, 16, v33
	v_and_b32_e32 v202, 0xffff0000, v34
	v_lshlrev_b32_e32 v203, 16, v34
	v_pk_fma_f32 v[136:137], v[124:125], v[136:137], v[148:149]
	v_and_b32_e32 v248, 0xffff0000, v35
	v_lshlrev_b32_e32 v249, 16, v35
	v_pk_fma_f32 v[138:139], v[124:125], v[138:139], v[146:147]
	v_and_b32_e32 v148, 0xffff0000, v36
	v_lshlrev_b32_e32 v149, 16, v36
	v_pk_fma_f32 v[140:141], v[124:125], v[140:141], v[202:203]
	v_and_b32_e32 v146, 0xffff0000, v37
	v_lshlrev_b32_e32 v147, 16, v37
	v_pk_fma_f32 v[142:143], v[124:125], v[142:143], v[248:249]
	v_and_b32_e32 v202, 0xffff0000, v38
	v_lshlrev_b32_e32 v203, 16, v38
	v_pk_fma_f32 v[144:145], v[124:125], v[144:145], v[148:149]
	v_and_b32_e32 v248, 0xffff0000, v39
	v_lshlrev_b32_e32 v249, 16, v39
	v_pk_fma_f32 v[132:133], v[124:125], v[132:133], v[146:147]
	v_pk_fma_f32 v[130:131], v[124:125], v[130:131], v[202:203]
	v_pk_fma_f32 v[128:129], v[124:125], v[128:129], v[248:249]
	global_load_dwordx4 v[32:35], v192, s[2:3]
	global_load_dwordx4 v[36:39], v134, s[2:3]
	s_add_u32 s2, s2, 0x4000
	s_addc_u32 s3, s3, 0
.Llb_proc_16:
	s_waitcnt vmcnt(30)
	v_and_b32_e32 v148, 0xffff0000, v24
	v_lshlrev_b32_e32 v149, 16, v24
	v_and_b32_e32 v146, 0xffff0000, v25
	v_lshlrev_b32_e32 v147, 16, v25
	v_and_b32_e32 v202, 0xffff0000, v26
	v_lshlrev_b32_e32 v203, 16, v26
	v_pk_fma_f32 v[136:137], v[124:125], v[136:137], v[148:149]
	v_and_b32_e32 v248, 0xffff0000, v27
	v_lshlrev_b32_e32 v249, 16, v27
	v_pk_fma_f32 v[138:139], v[124:125], v[138:139], v[146:147]
	v_and_b32_e32 v148, 0xffff0000, v28
	v_lshlrev_b32_e32 v149, 16, v28
	v_pk_fma_f32 v[140:141], v[124:125], v[140:141], v[202:203]
	v_and_b32_e32 v146, 0xffff0000, v29
	v_lshlrev_b32_e32 v147, 16, v29
	v_pk_fma_f32 v[142:143], v[124:125], v[142:143], v[248:249]
	v_and_b32_e32 v202, 0xffff0000, v30
	v_lshlrev_b32_e32 v203, 16, v30
	v_pk_fma_f32 v[144:145], v[124:125], v[144:145], v[148:149]
	v_and_b32_e32 v248, 0xffff0000, v31
	v_lshlrev_b32_e32 v249, 16, v31
	v_pk_fma_f32 v[132:133], v[124:125], v[132:133], v[146:147]
	v_pk_fma_f32 v[130:131], v[124:125], v[130:131], v[202:203]
	v_pk_fma_f32 v[128:129], v[124:125], v[128:129], v[248:249]
	global_load_dwordx4 v[24:27], v192, s[2:3]
	global_load_dwordx4 v[28:31], v134, s[2:3]
	s_add_u32 s2, s2, 0x4000
	s_addc_u32 s3, s3, 0
.Llb_proc_15:
	s_waitcnt vmcnt(30)
	v_and_b32_e32 v148, 0xffff0000, v188
	v_lshlrev_b32_e32 v149, 16, v188
	v_and_b32_e32 v146, 0xffff0000, v189
	v_lshlrev_b32_e32 v147, 16, v189
	v_and_b32_e32 v202, 0xffff0000, v190
	v_lshlrev_b32_e32 v203, 16, v190
	v_pk_fma_f32 v[136:137], v[124:125], v[136:137], v[148:149]
	v_and_b32_e32 v248, 0xffff0000, v191
	v_lshlrev_b32_e32 v249, 16, v191
	v_pk_fma_f32 v[138:139], v[124:125], v[138:139], v[146:147]
	v_and_b32_e32 v148, 0xffff0000, v222
	v_lshlrev_b32_e32 v149, 16, v222
	v_pk_fma_f32 v[140:141], v[124:125], v[140:141], v[202:203]
	v_and_b32_e32 v146, 0xffff0000, v223
	v_lshlrev_b32_e32 v147, 16, v223
	v_pk_fma_f32 v[142:143], v[124:125], v[142:143], v[248:249]
	v_and_b32_e32 v202, 0xffff0000, v224
	v_lshlrev_b32_e32 v203, 16, v224
	v_pk_fma_f32 v[144:145], v[124:125], v[144:145], v[148:149]
	v_and_b32_e32 v248, 0xffff0000, v225
	v_lshlrev_b32_e32 v249, 16, v225
	v_pk_fma_f32 v[132:133], v[124:125], v[132:133], v[146:147]
	v_pk_fma_f32 v[130:131], v[124:125], v[130:131], v[202:203]
	v_pk_fma_f32 v[128:129], v[124:125], v[128:129], v[248:249]
.Llb_proc_14:
	s_waitcnt vmcnt(28)
	v_and_b32_e32 v148, 0xffff0000, v240
	v_lshlrev_b32_e32 v149, 16, v240
	v_and_b32_e32 v146, 0xffff0000, v241
	v_lshlrev_b32_e32 v147, 16, v241
	v_and_b32_e32 v202, 0xffff0000, v242
	v_lshlrev_b32_e32 v203, 16, v242
	v_pk_fma_f32 v[136:137], v[124:125], v[136:137], v[148:149]
	v_and_b32_e32 v248, 0xffff0000, v243
	v_lshlrev_b32_e32 v249, 16, v243
	v_pk_fma_f32 v[138:139], v[124:125], v[138:139], v[146:147]
	v_and_b32_e32 v148, 0xffff0000, v244
	v_lshlrev_b32_e32 v149, 16, v244
	v_pk_fma_f32 v[140:141], v[124:125], v[140:141], v[202:203]
	v_and_b32_e32 v146, 0xffff0000, v245
	v_lshlrev_b32_e32 v147, 16, v245
	v_pk_fma_f32 v[142:143], v[124:125], v[142:143], v[248:249]
	v_and_b32_e32 v202, 0xffff0000, v246
	v_lshlrev_b32_e32 v203, 16, v246
	v_pk_fma_f32 v[144:145], v[124:125], v[144:145], v[148:149]
	v_and_b32_e32 v248, 0xffff0000, v247
	v_lshlrev_b32_e32 v249, 16, v247
	v_pk_fma_f32 v[132:133], v[124:125], v[132:133], v[146:147]
	v_pk_fma_f32 v[130:131], v[124:125], v[130:131], v[202:203]
	v_pk_fma_f32 v[128:129], v[124:125], v[128:129], v[248:249]
.Llb_proc_13:
	s_waitcnt vmcnt(26)
	v_and_b32_e32 v148, 0xffff0000, v232
	v_lshlrev_b32_e32 v149, 16, v232
	v_and_b32_e32 v146, 0xffff0000, v233
	v_lshlrev_b32_e32 v147, 16, v233
	v_and_b32_e32 v202, 0xffff0000, v234
	v_lshlrev_b32_e32 v203, 16, v234
	v_pk_fma_f32 v[136:137], v[124:125], v[136:137], v[148:149]
	v_and_b32_e32 v248, 0xffff0000, v235
	v_lshlrev_b32_e32 v249, 16, v235
	v_pk_fma_f32 v[138:139], v[124:125], v[138:139], v[146:147]
	v_and_b32_e32 v148, 0xffff0000, v236
	v_lshlrev_b32_e32 v149, 16, v236
	v_pk_fma_f32 v[140:141], v[124:125], v[140:141], v[202:203]
	v_and_b32_e32 v146, 0xffff0000, v237
	v_lshlrev_b32_e32 v147, 16, v237
	v_pk_fma_f32 v[142:143], v[124:125], v[142:143], v[248:249]
	v_and_b32_e32 v202, 0xffff0000, v238
	v_lshlrev_b32_e32 v203, 16, v238
	v_pk_fma_f32 v[144:145], v[124:125], v[144:145], v[148:149]
	v_and_b32_e32 v248, 0xffff0000, v239
	v_lshlrev_b32_e32 v249, 16, v239
	v_pk_fma_f32 v[132:133], v[124:125], v[132:133], v[146:147]
	v_pk_fma_f32 v[130:131], v[124:125], v[130:131], v[202:203]
	v_pk_fma_f32 v[128:129], v[124:125], v[128:129], v[248:249]
.Llb_proc_12:
	s_waitcnt vmcnt(24)
	v_and_b32_e32 v148, 0xffff0000, v214
	v_lshlrev_b32_e32 v149, 16, v214
	v_and_b32_e32 v146, 0xffff0000, v215
	v_lshlrev_b32_e32 v147, 16, v215
	v_and_b32_e32 v202, 0xffff0000, v216
	v_lshlrev_b32_e32 v203, 16, v216
	v_pk_fma_f32 v[136:137], v[124:125], v[136:137], v[148:149]
	v_and_b32_e32 v248, 0xffff0000, v217
	v_lshlrev_b32_e32 v249, 16, v217
	v_pk_fma_f32 v[138:139], v[124:125], v[138:139], v[146:147]
	v_and_b32_e32 v148, 0xffff0000, v218
	v_lshlrev_b32_e32 v149, 16, v218
	v_pk_fma_f32 v[140:141], v[124:125], v[140:141], v[202:203]
	v_and_b32_e32 v146, 0xffff0000, v219
	v_lshlrev_b32_e32 v147, 16, v219
	v_pk_fma_f32 v[142:143], v[124:125], v[142:143], v[248:249]
	v_and_b32_e32 v202, 0xffff0000, v220
	v_lshlrev_b32_e32 v203, 16, v220
	v_pk_fma_f32 v[144:145], v[124:125], v[144:145], v[148:149]
	v_and_b32_e32 v248, 0xffff0000, v221
	v_lshlrev_b32_e32 v249, 16, v221
	v_pk_fma_f32 v[132:133], v[124:125], v[132:133], v[146:147]
	v_pk_fma_f32 v[130:131], v[124:125], v[130:131], v[202:203]
	v_pk_fma_f32 v[128:129], v[124:125], v[128:129], v[248:249]
.Llb_proc_11:
	s_waitcnt vmcnt(22)
	v_and_b32_e32 v148, 0xffff0000, v206
	v_lshlrev_b32_e32 v149, 16, v206
	v_and_b32_e32 v146, 0xffff0000, v207
	v_lshlrev_b32_e32 v147, 16, v207
	v_and_b32_e32 v202, 0xffff0000, v208
	v_lshlrev_b32_e32 v203, 16, v208
	v_pk_fma_f32 v[136:137], v[124:125], v[136:137], v[148:149]
	v_and_b32_e32 v248, 0xffff0000, v209
	v_lshlrev_b32_e32 v249, 16, v209
	v_pk_fma_f32 v[138:139], v[124:125], v[138:139], v[146:147]
	v_and_b32_e32 v148, 0xffff0000, v210
	v_lshlrev_b32_e32 v149, 16, v210
	v_pk_fma_f32 v[140:141], v[124:125], v[140:141], v[202:203]
	v_and_b32_e32 v146, 0xffff0000, v211
	v_lshlrev_b32_e32 v147, 16, v211
	v_pk_fma_f32 v[142:143], v[124:125], v[142:143], v[248:249]
	v_and_b32_e32 v202, 0xffff0000, v212
	v_lshlrev_b32_e32 v203, 16, v212
	v_pk_fma_f32 v[144:145], v[124:125], v[144:145], v[148:149]
	v_and_b32_e32 v248, 0xffff0000, v213
	v_lshlrev_b32_e32 v249, 16, v213
	v_pk_fma_f32 v[132:133], v[124:125], v[132:133], v[146:147]
	v_pk_fma_f32 v[130:131], v[124:125], v[130:131], v[202:203]
	v_pk_fma_f32 v[128:129], v[124:125], v[128:129], v[248:249]
.Llb_proc_10:
	s_waitcnt vmcnt(20)
	v_and_b32_e32 v148, 0xffff0000, v194
	v_lshlrev_b32_e32 v149, 16, v194
	v_and_b32_e32 v146, 0xffff0000, v195
	v_lshlrev_b32_e32 v147, 16, v195
	v_and_b32_e32 v202, 0xffff0000, v196
	v_lshlrev_b32_e32 v203, 16, v196
	v_pk_fma_f32 v[136:137], v[124:125], v[136:137], v[148:149]
	v_and_b32_e32 v248, 0xffff0000, v197
	v_lshlrev_b32_e32 v249, 16, v197
	v_pk_fma_f32 v[138:139], v[124:125], v[138:139], v[146:147]
	v_and_b32_e32 v148, 0xffff0000, v198
	v_lshlrev_b32_e32 v149, 16, v198
	v_pk_fma_f32 v[140:141], v[124:125], v[140:141], v[202:203]
	v_and_b32_e32 v146, 0xffff0000, v199
	v_lshlrev_b32_e32 v147, 16, v199
	v_pk_fma_f32 v[142:143], v[124:125], v[142:143], v[248:249]
	v_and_b32_e32 v202, 0xffff0000, v200
	v_lshlrev_b32_e32 v203, 16, v200
	v_pk_fma_f32 v[144:145], v[124:125], v[144:145], v[148:149]
	v_and_b32_e32 v248, 0xffff0000, v201
	v_lshlrev_b32_e32 v249, 16, v201
	v_pk_fma_f32 v[132:133], v[124:125], v[132:133], v[146:147]
	v_pk_fma_f32 v[130:131], v[124:125], v[130:131], v[202:203]
	v_pk_fma_f32 v[128:129], v[124:125], v[128:129], v[248:249]
.Llb_proc_9:
	s_waitcnt vmcnt(18)
	v_and_b32_e32 v148, 0xffff0000, v180
	v_lshlrev_b32_e32 v149, 16, v180
	v_and_b32_e32 v146, 0xffff0000, v181
	v_lshlrev_b32_e32 v147, 16, v181
	v_and_b32_e32 v202, 0xffff0000, v182
	v_lshlrev_b32_e32 v203, 16, v182
	v_pk_fma_f32 v[136:137], v[124:125], v[136:137], v[148:149]
	v_and_b32_e32 v248, 0xffff0000, v183
	v_lshlrev_b32_e32 v249, 16, v183
	v_pk_fma_f32 v[138:139], v[124:125], v[138:139], v[146:147]
	v_and_b32_e32 v148, 0xffff0000, v184
	v_lshlrev_b32_e32 v149, 16, v184
	v_pk_fma_f32 v[140:141], v[124:125], v[140:141], v[202:203]
	v_and_b32_e32 v146, 0xffff0000, v185
	v_lshlrev_b32_e32 v147, 16, v185
	v_pk_fma_f32 v[142:143], v[124:125], v[142:143], v[248:249]
	v_and_b32_e32 v202, 0xffff0000, v186
	v_lshlrev_b32_e32 v203, 16, v186
	v_pk_fma_f32 v[144:145], v[124:125], v[144:145], v[148:149]
	v_and_b32_e32 v248, 0xffff0000, v187
	v_lshlrev_b32_e32 v249, 16, v187
	v_pk_fma_f32 v[132:133], v[124:125], v[132:133], v[146:147]
	v_pk_fma_f32 v[130:131], v[124:125], v[130:131], v[202:203]
	v_pk_fma_f32 v[128:129], v[124:125], v[128:129], v[248:249]
.Llb_proc_8:
	s_waitcnt vmcnt(16)
	v_and_b32_e32 v148, 0xffff0000, v172
	v_lshlrev_b32_e32 v149, 16, v172
	v_and_b32_e32 v146, 0xffff0000, v173
	v_lshlrev_b32_e32 v147, 16, v173
	v_and_b32_e32 v202, 0xffff0000, v174
	v_lshlrev_b32_e32 v203, 16, v174
	v_pk_fma_f32 v[136:137], v[124:125], v[136:137], v[148:149]
	v_and_b32_e32 v248, 0xffff0000, v175
	v_lshlrev_b32_e32 v249, 16, v175
	v_pk_fma_f32 v[138:139], v[124:125], v[138:139], v[146:147]
	v_and_b32_e32 v148, 0xffff0000, v176
	v_lshlrev_b32_e32 v149, 16, v176
	v_pk_fma_f32 v[140:141], v[124:125], v[140:141], v[202:203]
	v_and_b32_e32 v146, 0xffff0000, v177
	v_lshlrev_b32_e32 v147, 16, v177
	v_pk_fma_f32 v[142:143], v[124:125], v[142:143], v[248:249]
	v_and_b32_e32 v202, 0xffff0000, v178
	v_lshlrev_b32_e32 v203, 16, v178
	v_pk_fma_f32 v[144:145], v[124:125], v[144:145], v[148:149]
	v_and_b32_e32 v248, 0xffff0000, v179
	v_lshlrev_b32_e32 v249, 16, v179
	v_pk_fma_f32 v[132:133], v[124:125], v[132:133], v[146:147]
	v_pk_fma_f32 v[130:131], v[124:125], v[130:131], v[202:203]
	v_pk_fma_f32 v[128:129], v[124:125], v[128:129], v[248:249]
.Llb_proc_7:
	s_waitcnt vmcnt(14)
	v_and_b32_e32 v148, 0xffff0000, v164
	v_lshlrev_b32_e32 v149, 16, v164
	v_and_b32_e32 v146, 0xffff0000, v165
	v_lshlrev_b32_e32 v147, 16, v165
	v_and_b32_e32 v202, 0xffff0000, v166
	v_lshlrev_b32_e32 v203, 16, v166
	v_pk_fma_f32 v[136:137], v[124:125], v[136:137], v[148:149]
	v_and_b32_e32 v248, 0xffff0000, v167
	v_lshlrev_b32_e32 v249, 16, v167
	v_pk_fma_f32 v[138:139], v[124:125], v[138:139], v[146:147]
	v_and_b32_e32 v148, 0xffff0000, v168
	v_lshlrev_b32_e32 v149, 16, v168
	v_pk_fma_f32 v[140:141], v[124:125], v[140:141], v[202:203]
	v_and_b32_e32 v146, 0xffff0000, v169
	v_lshlrev_b32_e32 v147, 16, v169
	v_pk_fma_f32 v[142:143], v[124:125], v[142:143], v[248:249]
	v_and_b32_e32 v202, 0xffff0000, v170
	v_lshlrev_b32_e32 v203, 16, v170
	v_pk_fma_f32 v[144:145], v[124:125], v[144:145], v[148:149]
	v_and_b32_e32 v248, 0xffff0000, v171
	v_lshlrev_b32_e32 v249, 16, v171
	v_pk_fma_f32 v[132:133], v[124:125], v[132:133], v[146:147]
	v_pk_fma_f32 v[130:131], v[124:125], v[130:131], v[202:203]
	v_pk_fma_f32 v[128:129], v[124:125], v[128:129], v[248:249]
.Llb_proc_6:
	s_waitcnt vmcnt(12)
	v_and_b32_e32 v148, 0xffff0000, v156
	v_lshlrev_b32_e32 v149, 16, v156
	v_and_b32_e32 v146, 0xffff0000, v157
	v_lshlrev_b32_e32 v147, 16, v157
	v_and_b32_e32 v202, 0xffff0000, v158
	v_lshlrev_b32_e32 v203, 16, v158
	v_pk_fma_f32 v[136:137], v[124:125], v[136:137], v[148:149]
	v_and_b32_e32 v248, 0xffff0000, v159
	v_lshlrev_b32_e32 v249, 16, v159
	v_pk_fma_f32 v[138:139], v[124:125], v[138:139], v[146:147]
	v_and_b32_e32 v148, 0xffff0000, v160
	v_lshlrev_b32_e32 v149, 16, v160
	v_pk_fma_f32 v[140:141], v[124:125], v[140:141], v[202:203]
	v_and_b32_e32 v146, 0xffff0000, v161
	v_lshlrev_b32_e32 v147, 16, v161
	v_pk_fma_f32 v[142:143], v[124:125], v[142:143], v[248:249]
	v_and_b32_e32 v202, 0xffff0000, v162
	v_lshlrev_b32_e32 v203, 16, v162
	v_pk_fma_f32 v[144:145], v[124:125], v[144:145], v[148:149]
	v_and_b32_e32 v248, 0xffff0000, v163
	v_lshlrev_b32_e32 v249, 16, v163
	v_pk_fma_f32 v[132:133], v[124:125], v[132:133], v[146:147]
	v_pk_fma_f32 v[130:131], v[124:125], v[130:131], v[202:203]
	v_pk_fma_f32 v[128:129], v[124:125], v[128:129], v[248:249]
.Llb_proc_5:
	s_waitcnt vmcnt(10)
	v_and_b32_e32 v148, 0xffff0000, v104
	v_lshlrev_b32_e32 v149, 16, v104
	v_and_b32_e32 v146, 0xffff0000, v105
	v_lshlrev_b32_e32 v147, 16, v105
	v_and_b32_e32 v202, 0xffff0000, v106
	v_lshlrev_b32_e32 v203, 16, v106
	v_pk_fma_f32 v[136:137], v[124:125], v[136:137], v[148:149]
	v_and_b32_e32 v248, 0xffff0000, v107
	v_lshlrev_b32_e32 v249, 16, v107
	v_pk_fma_f32 v[138:139], v[124:125], v[138:139], v[146:147]
	v_and_b32_e32 v148, 0xffff0000, v108
	v_lshlrev_b32_e32 v149, 16, v108
	v_pk_fma_f32 v[140:141], v[124:125], v[140:141], v[202:203]
	v_and_b32_e32 v146, 0xffff0000, v109
	v_lshlrev_b32_e32 v147, 16, v109
	v_pk_fma_f32 v[142:143], v[124:125], v[142:143], v[248:249]
	v_and_b32_e32 v202, 0xffff0000, v110
	v_lshlrev_b32_e32 v203, 16, v110
	v_pk_fma_f32 v[144:145], v[124:125], v[144:145], v[148:149]
	v_and_b32_e32 v248, 0xffff0000, v111
	v_lshlrev_b32_e32 v249, 16, v111
	v_pk_fma_f32 v[132:133], v[124:125], v[132:133], v[146:147]
	v_pk_fma_f32 v[130:131], v[124:125], v[130:131], v[202:203]
	v_pk_fma_f32 v[128:129], v[124:125], v[128:129], v[248:249]
.Llb_proc_4:
	s_waitcnt vmcnt(8)
	v_and_b32_e32 v148, 0xffff0000, v96
	v_lshlrev_b32_e32 v149, 16, v96
	v_and_b32_e32 v146, 0xffff0000, v97
	v_lshlrev_b32_e32 v147, 16, v97
	v_and_b32_e32 v202, 0xffff0000, v98
	v_lshlrev_b32_e32 v203, 16, v98
	v_pk_fma_f32 v[136:137], v[124:125], v[136:137], v[148:149]
	v_and_b32_e32 v248, 0xffff0000, v99
	v_lshlrev_b32_e32 v249, 16, v99
	v_pk_fma_f32 v[138:139], v[124:125], v[138:139], v[146:147]
	v_and_b32_e32 v148, 0xffff0000, v100
	v_lshlrev_b32_e32 v149, 16, v100
	v_pk_fma_f32 v[140:141], v[124:125], v[140:141], v[202:203]
	v_and_b32_e32 v146, 0xffff0000, v101
	v_lshlrev_b32_e32 v147, 16, v101
	v_pk_fma_f32 v[142:143], v[124:125], v[142:143], v[248:249]
	v_and_b32_e32 v202, 0xffff0000, v102
	v_lshlrev_b32_e32 v203, 16, v102
	v_pk_fma_f32 v[144:145], v[124:125], v[144:145], v[148:149]
	v_and_b32_e32 v248, 0xffff0000, v103
	v_lshlrev_b32_e32 v249, 16, v103
	v_pk_fma_f32 v[132:133], v[124:125], v[132:133], v[146:147]
	v_pk_fma_f32 v[130:131], v[124:125], v[130:131], v[202:203]
	v_pk_fma_f32 v[128:129], v[124:125], v[128:129], v[248:249]
.Llb_proc_3:
	s_waitcnt vmcnt(6)
	v_and_b32_e32 v148, 0xffff0000, v88
	v_lshlrev_b32_e32 v149, 16, v88
	v_and_b32_e32 v146, 0xffff0000, v89
	v_lshlrev_b32_e32 v147, 16, v89
	v_and_b32_e32 v202, 0xffff0000, v90
	v_lshlrev_b32_e32 v203, 16, v90
	v_pk_fma_f32 v[136:137], v[124:125], v[136:137], v[148:149]
	v_and_b32_e32 v248, 0xffff0000, v91
	v_lshlrev_b32_e32 v249, 16, v91
	v_pk_fma_f32 v[138:139], v[124:125], v[138:139], v[146:147]
	v_and_b32_e32 v148, 0xffff0000, v92
	v_lshlrev_b32_e32 v149, 16, v92
	v_pk_fma_f32 v[140:141], v[124:125], v[140:141], v[202:203]
	v_and_b32_e32 v146, 0xffff0000, v93
	v_lshlrev_b32_e32 v147, 16, v93
	v_pk_fma_f32 v[142:143], v[124:125], v[142:143], v[248:249]
	v_and_b32_e32 v202, 0xffff0000, v94
	v_lshlrev_b32_e32 v203, 16, v94
	v_pk_fma_f32 v[144:145], v[124:125], v[144:145], v[148:149]
	v_and_b32_e32 v248, 0xffff0000, v95
	v_lshlrev_b32_e32 v249, 16, v95
	v_pk_fma_f32 v[132:133], v[124:125], v[132:133], v[146:147]
	v_pk_fma_f32 v[130:131], v[124:125], v[130:131], v[202:203]
	v_pk_fma_f32 v[128:129], v[124:125], v[128:129], v[248:249]
.Llb_proc_2:
	s_waitcnt vmcnt(4)
	v_and_b32_e32 v148, 0xffff0000, v40
	v_lshlrev_b32_e32 v149, 16, v40
	v_and_b32_e32 v146, 0xffff0000, v41
	v_lshlrev_b32_e32 v147, 16, v41
	v_and_b32_e32 v202, 0xffff0000, v42
	v_lshlrev_b32_e32 v203, 16, v42
	v_pk_fma_f32 v[136:137], v[124:125], v[136:137], v[148:149]
	v_and_b32_e32 v248, 0xffff0000, v43
	v_lshlrev_b32_e32 v249, 16, v43
	v_pk_fma_f32 v[138:139], v[124:125], v[138:139], v[146:147]
	v_and_b32_e32 v148, 0xffff0000, v44
	v_lshlrev_b32_e32 v149, 16, v44
	v_pk_fma_f32 v[140:141], v[124:125], v[140:141], v[202:203]
	v_and_b32_e32 v146, 0xffff0000, v45
	v_lshlrev_b32_e32 v147, 16, v45
	v_pk_fma_f32 v[142:143], v[124:125], v[142:143], v[248:249]
	v_and_b32_e32 v202, 0xffff0000, v46
	v_lshlrev_b32_e32 v203, 16, v46
	v_pk_fma_f32 v[144:145], v[124:125], v[144:145], v[148:149]
	v_and_b32_e32 v248, 0xffff0000, v47
	v_lshlrev_b32_e32 v249, 16, v47
	v_pk_fma_f32 v[132:133], v[124:125], v[132:133], v[146:147]
	v_pk_fma_f32 v[130:131], v[124:125], v[130:131], v[202:203]
	v_pk_fma_f32 v[128:129], v[124:125], v[128:129], v[248:249]
.Llb_proc_1:
	s_waitcnt vmcnt(2)
	v_and_b32_e32 v148, 0xffff0000, v32
	v_lshlrev_b32_e32 v149, 16, v32
	v_and_b32_e32 v146, 0xffff0000, v33
	v_lshlrev_b32_e32 v147, 16, v33
	v_and_b32_e32 v202, 0xffff0000, v34
	v_lshlrev_b32_e32 v203, 16, v34
	v_pk_fma_f32 v[136:137], v[124:125], v[136:137], v[148:149]
	v_and_b32_e32 v248, 0xffff0000, v35
	v_lshlrev_b32_e32 v249, 16, v35
	v_pk_fma_f32 v[138:139], v[124:125], v[138:139], v[146:147]
	v_and_b32_e32 v148, 0xffff0000, v36
	v_lshlrev_b32_e32 v149, 16, v36
	v_pk_fma_f32 v[140:141], v[124:125], v[140:141], v[202:203]
	v_and_b32_e32 v146, 0xffff0000, v37
	v_lshlrev_b32_e32 v147, 16, v37
	v_pk_fma_f32 v[142:143], v[124:125], v[142:143], v[248:249]
	v_and_b32_e32 v202, 0xffff0000, v38
	v_lshlrev_b32_e32 v203, 16, v38
	v_pk_fma_f32 v[144:145], v[124:125], v[144:145], v[148:149]
	v_and_b32_e32 v248, 0xffff0000, v39
	v_lshlrev_b32_e32 v249, 16, v39
	v_pk_fma_f32 v[132:133], v[124:125], v[132:133], v[146:147]
	v_pk_fma_f32 v[130:131], v[124:125], v[130:131], v[202:203]
	v_pk_fma_f32 v[128:129], v[124:125], v[128:129], v[248:249]
.Llb_proc_0:
	s_waitcnt vmcnt(0)
	v_and_b32_e32 v148, 0xffff0000, v24
	v_lshlrev_b32_e32 v149, 16, v24
	v_and_b32_e32 v146, 0xffff0000, v25
	v_lshlrev_b32_e32 v147, 16, v25
	v_and_b32_e32 v202, 0xffff0000, v26
	v_lshlrev_b32_e32 v203, 16, v26
	v_pk_fma_f32 v[136:137], v[124:125], v[136:137], v[148:149]
	v_and_b32_e32 v248, 0xffff0000, v27
	v_lshlrev_b32_e32 v249, 16, v27
	v_pk_fma_f32 v[138:139], v[124:125], v[138:139], v[146:147]
	v_and_b32_e32 v148, 0xffff0000, v28
	v_lshlrev_b32_e32 v149, 16, v28
	v_pk_fma_f32 v[140:141], v[124:125], v[140:141], v[202:203]
	v_and_b32_e32 v146, 0xffff0000, v29
	v_lshlrev_b32_e32 v147, 16, v29
	v_pk_fma_f32 v[142:143], v[124:125], v[142:143], v[248:249]
	v_and_b32_e32 v202, 0xffff0000, v30
	v_lshlrev_b32_e32 v203, 16, v30
	v_pk_fma_f32 v[144:145], v[124:125], v[144:145], v[148:149]
	v_and_b32_e32 v248, 0xffff0000, v31
	v_lshlrev_b32_e32 v249, 16, v31
	v_pk_fma_f32 v[132:133], v[124:125], v[132:133], v[146:147]
	v_pk_fma_f32 v[130:131], v[124:125], v[130:131], v[202:203]
	v_pk_fma_f32 v[128:129], v[124:125], v[128:129], v[248:249]
